# v025 + attention: PV LDS ring fill issued right after the QK MFMAs (latency under the softplus VALU); prompt path writes the K/V tile to LDS straight from the prefetch registers
# baseline (speedup 1.0000x reference)
; #define LAS __attribute__((address_space(3)))
; __device__ __forceinline__ unsigned cvt_pk_bf16(float lo, float hi) { unsigned r; asm volatile("v_cvt_pk_bf16_f32 %0, %1, %2" : "=v"(r) : "v"(lo), "v"(hi)); return r; }
; #define AT_ENSURE(pm_) do { const int _pm = (pm_); if (!((pseen >> _pm) & 1ull)) { if (tid < 64) pg8::panel_wait_wave0(g3cnt, _pm, 32u); __syncthreads(); pseen |= 1ull << _pm; } } while (0)
; __device__ __forceinline__ void attn_phase(const Params& p, LAS unsigned char* lds, int cidx) {
;     ...
;             __syncthreads();
;             {
;                 int alld = 1;
; #pragma unroll
;                 for (int w = 0; w < 8; ++w) alld &= misc[8 + w];
;                 if (alld) break;
;             }
; #pragma unroll
;             for (int i = 0; i < 2; ++i) {
;                 const int cid = tid + 512 * i, key = cid >> 4, d8 = (cid & 15) * 8;
;                 u32x4 kwv, vwv;
;                 if (!smp) { kwv = __builtin_bit_cast(u32x4, pf[i][0]); vwv = __builtin_bit_cast(u32x4, pf[i][2]); }
;                 else if (kt == 16) {
;                     if (key < 32) { const size_t off = (size_t)(MP + b * 32 + key) * DM + h * 128 + d8; kwv = *(const u32x4*)(kb + off); vwv = *(const u32x4*)(vb + off); }
;                     else { kwv = (u32x4){0u, 0u, 0u, 0u}; vwv = kwv; }
;                 } else {
;                     const f32x4 k0 = pf[i][0], k1 = pf[i][1], v0 = pf[i][2], v1 = pf[i][3];
;                     kwv.x = cvt_pk_bf16(k0[0], k0[1]); kwv.y = cvt_pk_bf16(k0[2], k0[3]); kwv.z = cvt_pk_bf16(k1[0], k1[1]); kwv.w = cvt_pk_bf16(k1[2], k1[3]);
;                     vwv.x = cvt_pk_bf16(v0[0], v0[1]); vwv.y = cvt_pk_bf16(v0[2], v0[3]); vwv.z = cvt_pk_bf16(v1[0], v1[1]); vwv.w = cvt_pk_bf16(v1[2], v1[3]);
;                 }
;                 *(LAS u32x4*)(Kl + key * AT_P + d8) = kwv; *(LAS u32x4*)(Vl + key * AT_P + d8) = vwv;
;             }
;             if (kt > 0 && !smp) AT_ENSURE(b * 8 + ((kt - 1) >> 2));
.LBB0_633:
	s_waitcnt lgkmcnt(0)
	s_barrier
	ds_read_b128 v[34:37], v0 offset:34848
	ds_read_b128 v[38:41], v0 offset:34864
	s_mov_b64 s[22:23], -1
	s_waitcnt lgkmcnt(1)
	v_and_b32_e32 v1, v34, v35
	v_and_b32_e32 v34, v36, v37
	v_and_b32_e32 v1, v1, v34
	s_waitcnt lgkmcnt(0)
	v_and_b32_e32 v34, v38, v39
	v_and_b32_e32 v35, v40, v41
	v_and_b32_e32 v1, v1, v34
	v_and_b32_e32 v1, v1, v35
	v_and_b32_e32 v1, 1, v1
	v_cmp_eq_u32_e32 vcc, 1, v1
	s_cbranch_vccnz .LBB0_631
	s_cmp_lg_u32 s33, 16
	v_cndmask_b32_e64 v1, 0, 1, s[2:3]
	s_cselect_b64 s[22:23], -1, 0
	v_cmp_ne_u32_e64 s[18:19], 1, v1
	s_andn2_b64 vcc, exec, s[2:3]
	s_mov_b64 s[24:25], -1
	s_cbranch_vccnz .LBB0_636
	s_cmp_lg_u32 s33, 0
	s_cselect_b64 s[22:23], -1, 0
	s_cmp_eq_u32 s33, 0
	s_cselect_b64 s[24:25], -1, 0
	s_or_b64 s[24:25], s[4:5], s[24:25]
	s_and_b64 vcc, exec, s[24:25]
	s_waitcnt vmcnt(1)
	ds_write_b128 v170, v[2:5]
	s_waitcnt vmcnt(0)
	ds_write_b128 v170, v[10:13] offset:17408
	ds_write_b128 v172, v[18:21]
	ds_write_b128 v172, v[26:29] offset:17408
	s_cbranch_vccnz .LBB0_654
	s_branch .Latt_653

; #define AT_ENSURE(pm_) do { const int _pm = (pm_); if (!((pseen >> _pm) & 1ull)) { if (tid < 64) pg8::panel_wait_wave0(g3cnt, _pm, 32u); __syncthreads(); pseen |= 1ull << _pm; } } while (0)
; __device__ __forceinline__ void attn_phase(const Params& p, LAS unsigned char* lds, int cidx) {
;     ...
;             if (kt > 0 && !smp) AT_ENSURE(b * 8 + ((kt - 1) >> 2));
.Latt_653:
	s_add_i32 s24, s33, -1
	s_lshr_b32 s28, s24, 2
	s_add_i32 s28, s28, s6
	s_lshl_b64 s[24:25], 1, s28
	s_and_b64 s[26:27], s[24:25], s[88:89]
	s_cmp_lg_u64 s[26:27], 0
	s_cbranch_scc0 .LBB0_663

; #define LAS __attribute__((address_space(3)))
; __device__ __forceinline__ void attn_phase(const Params& p, LAS unsigned char* lds, int cidx) {
;     ...
;                 for (int kk = 0; kk < 4; ++kk)
; #pragma unroll
;                     for (int n = 0; n < 4; ++n) {
;                         const bf16x8 kf = *(const LAS bf16x8*)(Kl + (16 * (fr >> 2) + 4 * n + (fr & 3)) * AT_P + 32 * kk + 8 * fq);
;                         st[0][n] = __builtin_amdgcn_mfma_f32_16x16x32_bf16(kf, qf[0][kk], st[0][n], 0, 0, 0);
;                         st[1][n] = __builtin_amdgcn_mfma_f32_16x16x32_bf16(kf, qf[1][kk], st[1][n], 0, 0, 0);
;                     }
;                 bf16x8 pb[2][2];
;                 {
;                     const int s0 = kt * 64 + 16 * fq, tq0 = tpos0 + fr, tq1 = tpos0 + 16 + fr;
;                     f32x2 run = (f32x2){0.f, 0.f};
; #pragma unroll
;     ...
;                         const f32x2 xv = (f32x2){st[0][idx >> 2][idx & 3], st[1][idx >> 2][idx & 3]};
;                         const f32x2 ax = __builtin_elementwise_abs(xv);
;                         f32x2 e; e.x = __builtin_amdgcn_exp2f(-ax.x); e.y = __builtin_amdgcn_exp2f(-ax.y);
;                         const f32x2 e1 = e + 1.0f;
;                         f32x2 lg; lg.x = __builtin_amdgcn_logf(e1.x); lg.y = __builtin_amdgcn_logf(e1.y);
;                         const f32x2 sp = __builtin_elementwise_max(xv, (f32x2){0.f, 0.f}) + lg;
;                         const f32x2 lw = (xv - sp) + run;
;                         st[0][idx >> 2][idx & 3] = lw.x; st[1][idx >> 2][idx & 3] = lw.y;
.LBB0_674:
	s_xor_b64 s[20:21], s[20:21], -1
	s_mov_b64 s[18:19], -1
	s_waitcnt lgkmcnt(0)
	s_barrier
	s_and_saveexec_b64 s[78:79], s[20:21]
	s_cbranch_execz .LBB0_680
	s_lshl_b32 s20, s33, 6
	s_cmp_ge_i32 s20, s7
	s_mov_b64 s[18:19], 0
	s_cbranch_scc1 .LBB0_679
	s_add_i32 s32, s20, 94
	s_cmp_lt_i32 s32, s7
	s_cbranch_scc0 .Latt_masked
	ds_read_b128 v[218:221], v171
	ds_read_b128 v[222:225], v171 offset:1088
	ds_read_b128 v[226:229], v171 offset:2176
	ds_read_b128 v[230:233], v171 offset:3264
	ds_read_b128 v[236:239], v171 offset:64
	ds_read_b128 v[240:243], v171 offset:1152
	ds_read_b128 v[244:247], v171 offset:2240
	ds_read_b128 v[248:251], v171 offset:3328
	s_waitcnt lgkmcnt(7)
	v_mfma_f32_16x16x32_bf16 v[34:37], v[218:221], v[98:101], 0
	v_mfma_f32_16x16x32_bf16 v[38:41], v[218:221], v[118:121], 0
	ds_read_b128 v[218:221], v171 offset:128
	s_waitcnt lgkmcnt(7)
	v_mfma_f32_16x16x32_bf16 v[42:45], v[222:225], v[98:101], 0
	v_mfma_f32_16x16x32_bf16 v[46:49], v[222:225], v[118:121], 0
	ds_read_b128 v[222:225], v171 offset:1216
	s_waitcnt lgkmcnt(7)
	v_mfma_f32_16x16x32_bf16 v[50:53], v[226:229], v[98:101], 0
	v_mfma_f32_16x16x32_bf16 v[54:57], v[226:229], v[118:121], 0
	ds_read_b128 v[226:229], v171 offset:2304
	s_waitcnt lgkmcnt(7)
	v_mfma_f32_16x16x32_bf16 v[190:193], v[230:233], v[98:101], 0
	v_mfma_f32_16x16x32_bf16 v[206:209], v[230:233], v[118:121], 0
	ds_read_b128 v[230:233], v171 offset:3392
	s_waitcnt lgkmcnt(7)
	v_mfma_f32_16x16x32_bf16 v[34:37], v[236:239], v[102:105], v[34:37]
	v_mfma_f32_16x16x32_bf16 v[38:41], v[236:239], v[122:125], v[38:41]
	ds_read_b128 v[236:239], v171 offset:192
	s_waitcnt lgkmcnt(7)
	v_mfma_f32_16x16x32_bf16 v[42:45], v[240:243], v[102:105], v[42:45]
	v_mfma_f32_16x16x32_bf16 v[46:49], v[240:243], v[122:125], v[46:49]
	ds_read_b128 v[240:243], v171 offset:1280
	s_waitcnt lgkmcnt(7)
	v_mfma_f32_16x16x32_bf16 v[50:53], v[244:247], v[102:105], v[50:53]
	v_mfma_f32_16x16x32_bf16 v[54:57], v[244:247], v[122:125], v[54:57]
	ds_read_b128 v[244:247], v171 offset:2368
	s_waitcnt lgkmcnt(7)
	v_mfma_f32_16x16x32_bf16 v[190:193], v[248:251], v[102:105], v[190:193]
	v_mfma_f32_16x16x32_bf16 v[206:209], v[248:251], v[122:125], v[206:209]
	ds_read_b128 v[248:251], v171 offset:3456
	s_waitcnt lgkmcnt(7)
	v_mfma_f32_16x16x32_bf16 v[34:37], v[218:221], v[106:109], v[34:37]
	v_mfma_f32_16x16x32_bf16 v[38:41], v[218:221], v[126:129], v[38:41]
	s_waitcnt lgkmcnt(6)
	v_mfma_f32_16x16x32_bf16 v[42:45], v[222:225], v[106:109], v[42:45]
	v_mfma_f32_16x16x32_bf16 v[46:49], v[222:225], v[126:129], v[46:49]
	s_waitcnt lgkmcnt(5)
	v_mfma_f32_16x16x32_bf16 v[50:53], v[226:229], v[106:109], v[50:53]
	v_mfma_f32_16x16x32_bf16 v[54:57], v[226:229], v[126:129], v[54:57]
	s_waitcnt lgkmcnt(4)
	v_mfma_f32_16x16x32_bf16 v[190:193], v[230:233], v[106:109], v[190:193]
	v_mfma_f32_16x16x32_bf16 v[206:209], v[230:233], v[126:129], v[206:209]
	s_waitcnt lgkmcnt(3)
	v_mfma_f32_16x16x32_bf16 v[34:37], v[236:239], v[110:113], v[34:37]
	v_mfma_f32_16x16x32_bf16 v[38:41], v[236:239], v[130:133], v[38:41]
	s_waitcnt lgkmcnt(2)
	v_mfma_f32_16x16x32_bf16 v[42:45], v[240:243], v[110:113], v[42:45]
	v_mfma_f32_16x16x32_bf16 v[46:49], v[240:243], v[130:133], v[46:49]
	s_waitcnt lgkmcnt(1)
	v_mfma_f32_16x16x32_bf16 v[50:53], v[244:247], v[110:113], v[50:53]
	v_mfma_f32_16x16x32_bf16 v[54:57], v[244:247], v[130:133], v[54:57]
	s_waitcnt lgkmcnt(0)
	v_mfma_f32_16x16x32_bf16 v[190:193], v[248:251], v[110:113], v[190:193]
	v_mfma_f32_16x16x32_bf16 v[206:209], v[248:251], v[130:133], v[206:209]
	ds_read_b64_tr_b16 v[218:219], v173 offset:17408
	ds_read_b64_tr_b16 v[220:221], v173 offset:18496
	ds_read_b64_tr_b16 v[222:223], v173 offset:17440
	ds_read_b64_tr_b16 v[224:225], v173 offset:18528
	ds_read_b64_tr_b16 v[226:227], v173 offset:17472
	ds_read_b64_tr_b16 v[228:229], v173 offset:18560
	ds_read_b64_tr_b16 v[230:231], v173 offset:17504
	ds_read_b64_tr_b16 v[232:233], v173 offset:18592
	ds_read_b64_tr_b16 v[236:237], v173 offset:17536
	ds_read_b64_tr_b16 v[238:239], v173 offset:18624
	ds_read_b64_tr_b16 v[240:241], v173 offset:17568
	ds_read_b64_tr_b16 v[242:243], v173 offset:18656
	s_nop 6
	v_exp_f32_e64 v62, -|v193|
	v_mov_b32_e32 v60, v193
	v_exp_f32_e64 v63, -|v209|
	v_max_f32_e32 v65, 0, v209
	v_pk_add_f32 v[62:63], v[62:63], 1.0 op_sel_hi:[1,0]
	v_max_f32_e32 v64, 0, v193
	v_log_f32_e32 v62, v62
	v_log_f32_e32 v63, v63
	v_mov_b32_e32 v61, v209
	v_mov_b32_e32 v193, v208
	v_pk_add_f32 v[62:63], v[64:65], v[62:63]
	v_pk_add_f32 v[60:61], v[60:61], v[62:63] neg_lo:[0,1] neg_hi:[0,1]
	v_pk_add_f32 v[64:65], v[62:63], 0 op_sel_hi:[1,0] neg_lo:[1,0] neg_hi:[1,0]
	v_exp_f32_e64 v62, -|v192|
	v_exp_f32_e64 v63, -|v208|
	v_max_f32_e32 v209, 0, v208
	v_pk_add_f32 v[62:63], v[62:63], 1.0 op_sel_hi:[1,0]
	v_max_f32_e32 v208, 0, v192
	v_log_f32_e32 v62, v62
	v_log_f32_e32 v63, v63
	v_pk_add_f32 v[60:61], v[60:61], 0 op_sel_hi:[1,0]
	v_pk_add_f32 v[208:209], v[208:209], v[62:63]
	s_nop 0
	v_pk_add_f32 v[62:63], v[192:193], v[208:209] neg_lo:[0,1] neg_hi:[0,1]
	v_pk_add_f32 v[62:63], v[62:63], v[64:65]
	v_mov_b32_e32 v192, v208
	v_mov_b32_e32 v193, v209
	v_exp_f32_e64 v208, -|v191|
	v_exp_f32_e64 v209, -|v207|
	v_pk_add_f32 v[192:193], v[64:65], v[192:193] neg_lo:[0,1] neg_hi:[0,1]
	v_mov_b32_e32 v64, v191
	v_mov_b32_e32 v65, v207
	v_pk_add_f32 v[208:209], v[208:209], 1.0 op_sel_hi:[1,0]
	v_log_f32_e32 v208, v208
	v_log_f32_e32 v209, v209
	v_max_f32_e32 v211, 0, v207
	v_max_f32_e32 v210, 0, v191
	v_pk_add_f32 v[208:209], v[210:211], v[208:209]
	v_pk_add_f32 v[64:65], v[64:65], v[208:209] neg_lo:[0,1] neg_hi:[0,1]
	v_pk_add_f32 v[64:65], v[64:65], v[192:193]
; __device__ __forceinline__ void attn_phase(const Params& p, LAS unsigned char* lds, int cidx) {
;     ...
;                         const f32x2 xv = (f32x2){st[0][idx >> 2][idx & 3], st[1][idx >> 2][idx & 3]};
;                         const f32x2 ax = __builtin_elementwise_abs(xv);
;                         f32x2 e; e.x = __builtin_amdgcn_exp2f(-ax.x); e.y = __builtin_amdgcn_exp2f(-ax.y);
;                         const f32x2 e1 = e + 1.0f;
;                         f32x2 lg; lg.x = __builtin_amdgcn_logf(e1.x); lg.y = __builtin_amdgcn_logf(e1.y);
;                         const f32x2 sp = __builtin_elementwise_max(xv, (f32x2){0.f, 0.f}) + lg;
;                         const f32x2 lw = (xv - sp) + run;
;                         st[0][idx >> 2][idx & 3] = lw.x; st[1][idx >> 2][idx & 3] = lw.y;
;                         f32x2 dec; dec.x = (s0 + idx) < tq0 ? sp.x : 0.f; dec.y = (s0 + idx) < tq1 ? sp.y : 0.f;
;                         run = run - dec;
;                     }
;                     f32x2 t16, t32, t48;
;                     t16.x = __shfl(run.x, (lane + 16) & 63); t16.y = __shfl(run.y, (lane + 16) & 63);
;                     t32.x = __shfl(run.x, (lane + 32) & 63); t32.y = __shfl(run.y, (lane + 32) & 63);
;                     t48.x = __shfl(run.x, (lane + 48) & 63); t48.y = __shfl(run.y, (lane + 48) & 63);
	v_pk_add_f32 v[192:193], v[192:193], v[208:209] neg_lo:[0,1] neg_hi:[0,1]
	v_exp_f32_e64 v208, -|v190|
	v_exp_f32_e64 v209, -|v206|
	v_mov_b32_e32 v191, v206
	v_max_f32_e32 v207, 0, v206
	v_pk_add_f32 v[208:209], v[208:209], 1.0 op_sel_hi:[1,0]
	v_log_f32_e32 v208, v208
	v_log_f32_e32 v209, v209
	v_max_f32_e32 v206, 0, v190
	v_pk_add_f32 v[206:207], v[206:207], v[208:209]
	v_exp_f32_e64 v208, -|v53|
	v_exp_f32_e64 v209, -|v57|
	v_pk_add_f32 v[190:191], v[190:191], v[206:207] neg_lo:[0,1] neg_hi:[0,1]
	v_pk_add_f32 v[208:209], v[208:209], 1.0 op_sel_hi:[1,0]
	v_pk_add_f32 v[190:191], v[190:191], v[192:193]
	v_log_f32_e32 v208, v208
	v_log_f32_e32 v209, v209
	v_pk_add_f32 v[206:207], v[192:193], v[206:207] neg_lo:[0,1] neg_hi:[0,1]
	v_mov_b32_e32 v192, v53
	v_mov_b32_e32 v193, v57
	v_max_f32_e32 v211, 0, v57
	v_max_f32_e32 v210, 0, v53
	v_pk_add_f32 v[208:209], v[210:211], v[208:209]
	v_pk_add_f32 v[192:193], v[192:193], v[208:209] neg_lo:[0,1] neg_hi:[0,1]
	v_pk_add_f32 v[192:193], v[192:193], v[206:207]
	v_pk_add_f32 v[206:207], v[206:207], v[208:209] neg_lo:[0,1] neg_hi:[0,1]
	v_exp_f32_e64 v208, -|v52|
	v_exp_f32_e64 v209, -|v56|
	v_mov_b32_e32 v53, v56
	v_max_f32_e32 v57, 0, v56
	v_pk_add_f32 v[208:209], v[208:209], 1.0 op_sel_hi:[1,0]
	v_log_f32_e32 v208, v208
	v_log_f32_e32 v209, v209
	v_max_f32_e32 v56, 0, v52
	v_pk_add_f32 v[56:57], v[56:57], v[208:209]
	v_exp_f32_e64 v208, -|v51|
	v_exp_f32_e64 v209, -|v55|
	v_pk_add_f32 v[52:53], v[52:53], v[56:57] neg_lo:[0,1] neg_hi:[0,1]
	v_pk_add_f32 v[208:209], v[208:209], 1.0 op_sel_hi:[1,0]
	v_pk_add_f32 v[52:53], v[52:53], v[206:207]
	v_log_f32_e32 v208, v208
	v_log_f32_e32 v209, v209
	v_pk_add_f32 v[206:207], v[206:207], v[56:57] neg_lo:[0,1] neg_hi:[0,1]
	v_mov_b32_e32 v56, v51
	v_mov_b32_e32 v57, v55
	v_max_f32_e32 v211, 0, v55
	v_max_f32_e32 v210, 0, v51
	v_pk_add_f32 v[208:209], v[210:211], v[208:209]
	v_pk_add_f32 v[56:57], v[56:57], v[208:209] neg_lo:[0,1] neg_hi:[0,1]
	v_pk_add_f32 v[56:57], v[56:57], v[206:207]
	v_pk_add_f32 v[206:207], v[206:207], v[208:209] neg_lo:[0,1] neg_hi:[0,1]
	v_exp_f32_e64 v208, -|v50|
	v_exp_f32_e64 v209, -|v54|
	v_mov_b32_e32 v51, v54
	v_max_f32_e32 v55, 0, v54
	v_pk_add_f32 v[208:209], v[208:209], 1.0 op_sel_hi:[1,0]
	v_log_f32_e32 v208, v208
	v_log_f32_e32 v209, v209
	v_max_f32_e32 v54, 0, v50
	v_pk_add_f32 v[54:55], v[54:55], v[208:209]
	v_exp_f32_e64 v208, -|v45|
	v_exp_f32_e64 v209, -|v49|
	v_pk_add_f32 v[50:51], v[50:51], v[54:55] neg_lo:[0,1] neg_hi:[0,1]
	v_pk_add_f32 v[208:209], v[208:209], 1.0 op_sel_hi:[1,0]
	v_pk_add_f32 v[50:51], v[50:51], v[206:207]
	v_log_f32_e32 v208, v208
	v_log_f32_e32 v209, v209
	v_pk_add_f32 v[206:207], v[206:207], v[54:55] neg_lo:[0,1] neg_hi:[0,1]
	v_mov_b32_e32 v54, v45
	v_mov_b32_e32 v55, v49
	v_max_f32_e32 v211, 0, v49
	v_max_f32_e32 v210, 0, v45
	v_pk_add_f32 v[208:209], v[210:211], v[208:209]
	v_pk_add_f32 v[54:55], v[54:55], v[208:209] neg_lo:[0,1] neg_hi:[0,1]
	v_pk_add_f32 v[54:55], v[54:55], v[206:207]
	v_pk_add_f32 v[206:207], v[206:207], v[208:209] neg_lo:[0,1] neg_hi:[0,1]
	v_exp_f32_e64 v208, -|v44|
	v_exp_f32_e64 v209, -|v48|
	v_mov_b32_e32 v45, v48
	v_max_f32_e32 v49, 0, v48
	v_pk_add_f32 v[208:209], v[208:209], 1.0 op_sel_hi:[1,0]
	v_log_f32_e32 v208, v208
	v_log_f32_e32 v209, v209
	v_max_f32_e32 v48, 0, v44
	v_pk_add_f32 v[48:49], v[48:49], v[208:209]
	v_exp_f32_e64 v208, -|v43|
	v_exp_f32_e64 v209, -|v47|
	v_pk_add_f32 v[44:45], v[44:45], v[48:49] neg_lo:[0,1] neg_hi:[0,1]
	v_pk_add_f32 v[208:209], v[208:209], 1.0 op_sel_hi:[1,0]
	v_pk_add_f32 v[44:45], v[44:45], v[206:207]
	v_log_f32_e32 v208, v208
	v_log_f32_e32 v209, v209
	v_pk_add_f32 v[206:207], v[206:207], v[48:49] neg_lo:[0,1] neg_hi:[0,1]
	v_mov_b32_e32 v48, v43
	v_mov_b32_e32 v49, v47
	v_max_f32_e32 v211, 0, v47
	v_max_f32_e32 v210, 0, v43
	v_pk_add_f32 v[208:209], v[210:211], v[208:209]
	v_pk_add_f32 v[48:49], v[48:49], v[208:209] neg_lo:[0,1] neg_hi:[0,1]
	v_pk_add_f32 v[48:49], v[48:49], v[206:207]
	v_pk_add_f32 v[206:207], v[206:207], v[208:209] neg_lo:[0,1] neg_hi:[0,1]
	v_exp_f32_e64 v208, -|v42|
	v_exp_f32_e64 v209, -|v46|
	v_mov_b32_e32 v43, v46
	v_max_f32_e32 v47, 0, v46
	v_pk_add_f32 v[208:209], v[208:209], 1.0 op_sel_hi:[1,0]
	v_log_f32_e32 v208, v208
	v_log_f32_e32 v209, v209
	v_max_f32_e32 v46, 0, v42
	v_pk_add_f32 v[208:209], v[46:47], v[208:209]
	s_nop 0
	v_pk_add_f32 v[42:43], v[42:43], v[208:209] neg_lo:[0,1] neg_hi:[0,1]
	s_nop 0
	v_pk_add_f32 v[46:47], v[42:43], v[206:207]
	s_nop 0
	v_mov_b32_e32 v42, v208
	v_mov_b32_e32 v43, v209
	v_exp_f32_e64 v208, -|v37|
	v_exp_f32_e64 v209, -|v41|
	v_pk_add_f32 v[42:43], v[206:207], v[42:43] neg_lo:[0,1] neg_hi:[0,1]
	v_mov_b32_e32 v206, v37
	v_mov_b32_e32 v207, v41
	v_pk_add_f32 v[208:209], v[208:209], 1.0 op_sel_hi:[1,0]
	v_log_f32_e32 v208, v208
	v_log_f32_e32 v209, v209
	v_max_f32_e32 v211, 0, v41
	v_max_f32_e32 v210, 0, v37
	v_pk_add_f32 v[208:209], v[210:211], v[208:209]
	v_pk_add_f32 v[206:207], v[206:207], v[208:209] neg_lo:[0,1] neg_hi:[0,1]
	v_pk_add_f32 v[206:207], v[206:207], v[42:43]
	v_pk_add_f32 v[42:43], v[42:43], v[208:209] neg_lo:[0,1] neg_hi:[0,1]
	v_exp_f32_e64 v208, -|v36|
	v_exp_f32_e64 v209, -|v40|
	v_mov_b32_e32 v37, v40
	v_max_f32_e32 v41, 0, v40
	v_pk_add_f32 v[208:209], v[208:209], 1.0 op_sel_hi:[1,0]
	v_log_f32_e32 v208, v208
	v_log_f32_e32 v209, v209
	v_max_f32_e32 v40, 0, v36
	v_pk_add_f32 v[40:41], v[40:41], v[208:209]
	v_exp_f32_e64 v208, -|v35|
	v_exp_f32_e64 v209, -|v39|
	v_pk_add_f32 v[36:37], v[36:37], v[40:41] neg_lo:[0,1] neg_hi:[0,1]
	v_pk_add_f32 v[208:209], v[208:209], 1.0 op_sel_hi:[1,0]
	v_pk_add_f32 v[36:37], v[36:37], v[42:43]
	v_log_f32_e32 v208, v208
	v_log_f32_e32 v209, v209
	v_pk_add_f32 v[40:41], v[42:43], v[40:41] neg_lo:[0,1] neg_hi:[0,1]
	v_mov_b32_e32 v42, v35
	v_mov_b32_e32 v43, v39
	v_max_f32_e32 v211, 0, v39
	v_max_f32_e32 v210, 0, v35
	v_pk_add_f32 v[208:209], v[210:211], v[208:209]
	v_pk_add_f32 v[42:43], v[42:43], v[208:209] neg_lo:[0,1] neg_hi:[0,1]
	v_pk_add_f32 v[210:211], v[42:43], v[40:41]
	v_mov_b32_e32 v42, v208
	v_mov_b32_e32 v43, v209
	v_pk_add_f32 v[40:41], v[40:41], v[42:43] neg_lo:[0,1] neg_hi:[0,1]
	v_exp_f32_e64 v42, -|v34|
	v_exp_f32_e64 v43, -|v38|
	v_mov_b32_e32 v35, v38
	v_max_f32_e32 v39, 0, v38
	v_pk_add_f32 v[42:43], v[42:43], 1.0 op_sel_hi:[1,0]
	v_log_f32_e32 v42, v42
	v_log_f32_e32 v43, v43
	v_max_f32_e32 v38, 0, v34
	v_or_b32_e32 v1, v201, v196
	v_lshlrev_b32_e32 v1, 2, v1
	v_pk_add_f32 v[38:39], v[38:39], v[42:43]
	v_xor_b32_e32 v1, 0x80, v1
	v_pk_add_f32 v[34:35], v[34:35], v[38:39] neg_lo:[0,1] neg_hi:[0,1]
	v_pk_add_f32 v[38:39], v[40:41], v[38:39] neg_lo:[0,1] neg_hi:[0,1]
	v_pk_add_f32 v[34:35], v[34:35], v[40:41]
	ds_bpermute_b32 v40, v202, v38
	ds_bpermute_b32 v41, v202, v39
	ds_bpermute_b32 v42, v1, v38
	ds_bpermute_b32 v43, v1, v39
	ds_bpermute_b32 v208, v203, v38
	ds_bpermute_b32 v209, v203, v39
	s_waitcnt lgkmcnt(4)
; __device__ __forceinline__ void attn_phase(const Params& p, LAS unsigned char* lds, int cidx) {
;     ...
;                     const f32x2 higher = (fq < 3 ? t16 : z2) + (fq < 2 ? t32 : z2) + (fq < 1 ? t48 : z2);
;                     const f32x2 base = (f32x2){C[0], C[1]} + higher;
;                     const f32x2 tot = (run + t16) + (t32 + t48);
;                     C[0] += tot.x; C[1] += tot.y;
;                     float w0[16], w1[16];
; #pragma unroll
;                     for (int idx = 0; idx < 16; ++idx) {
;                         const f32x2 a2 = (f32x2){st[0][idx >> 2][idx & 3], st[1][idx >> 2][idx & 3]} + base;
;                         w0[idx] = (s0 + idx) < tq0 ? __builtin_amdgcn_exp2f(a2.x) : 0.f;
;                         w1[idx] = (s0 + idx) < tq1 ? __builtin_amdgcn_exp2f(a2.y) : 0.f;
;                     }
; #pragma unroll
;                     for (int k2 = 0; k2 < 2; ++k2) {
;                         u32x4 pw; pw.x = cvt_pk_bf16(w0[8 * k2 + 0], w0[8 * k2 + 1]); pw.y = cvt_pk_bf16(w0[8 * k2 + 2], w0[8 * k2 + 3]); pw.z = cvt_pk_bf16(w0[8 * k2 + 4], w0[8 * k2 + 5]); pw.w = cvt_pk_bf16(w0[8 * k2 + 6], w0[8 * k2 + 7]);
;                         pb[0][k2] = __builtin_bit_cast(bf16x8, pw);
;                         u32x4 pv; pv.x = cvt_pk_bf16(w1[8 * k2 + 0], w1[8 * k2 + 1]); pv.y = cvt_pk_bf16(w1[8 * k2 + 2], w1[8 * k2 + 3]); pv.z = cvt_pk_bf16(w1[8 * k2 + 4], w1[8 * k2 + 5]); pv.w = cvt_pk_bf16(w1[8 * k2 + 6], w1[8 * k2 + 7]);
;                         pb[1][k2] = __builtin_bit_cast(bf16x8, pv);
;                     }
;                 }
; #pragma unroll
;                 for (int k2 = 0; k2 < 2; ++k2)
; #pragma unroll
;                     for (int dt = 0; dt < 8; ++dt) {
;                         const LAS bf16_t* a0 = Vl + (16 * fq + 8 * k2 + (fr >> 2)) * AT_P + 16 * dt + 4 * (fr & 3);
;                         const s16x4 lo = __builtin_amdgcn_ds_read_tr16_b64_v4i16((LAS s16x4*)a0), hi = __builtin_amdgcn_ds_read_tr16_b64_v4i16((LAS s16x4*)(a0 + 4 * AT_P));
;                         const bf16x8 vf = (bf16x8){lo[0], lo[1], lo[2], lo[3], hi[0], hi[1], hi[2], hi[3]};
;                         o[0][dt] = __builtin_amdgcn_mfma_f32_16x16x32_bf16(vf, pb[0][k2], o[0][dt], 0, 0, 0);
;                         o[1][dt] = __builtin_amdgcn_mfma_f32_16x16x32_bf16(vf, pb[1][k2], o[1][dt], 0, 0, 0);
;                     }
	v_cndmask_b32_e64 v213, v41, 0, s[8:9]
	v_cndmask_b32_e64 v212, v40, 0, s[8:9]
	s_waitcnt lgkmcnt(2)
	v_cndmask_b32_e64 v215, 0, v43, s[10:11]
	v_cndmask_b32_e64 v214, 0, v42, s[10:11]
	v_pk_add_f32 v[212:213], v[212:213], v[214:215]
	s_waitcnt lgkmcnt(0)
	v_cndmask_b32_e64 v215, 0, v209, s[12:13]
	v_cndmask_b32_e64 v214, 0, v208, s[12:13]
	v_pk_add_f32 v[212:213], v[212:213], v[214:215]
	v_pk_add_f32 v[38:39], v[38:39], v[40:41]
	v_pk_add_f32 v[212:213], v[58:59], v[212:213]
	v_pk_add_f32 v[40:41], v[42:43], v[208:209]
	v_pk_add_f32 v[34:35], v[212:213], v[34:35]
	v_pk_add_f32 v[42:43], v[40:41], v[38:39]
	v_exp_f32_e32 v1, v34
	v_exp_f32_e32 v34, v35
	v_pk_add_f32 v[58:59], v[58:59], v[42:43]
	v_mov_b32_e32 v38, v34
	v_pk_add_f32 v[34:35], v[212:213], v[210:211]
	s_nop 0
	v_exp_f32_e32 v34, v34
	s_nop 0
	v_mov_b32_e32 v39, v34
	v_exp_f32_e32 v34, v35
	s_nop 0
	v_mov_b32_e32 v40, v34
	v_pk_add_f32 v[34:35], v[212:213], v[36:37]
	s_nop 0
	v_exp_f32_e32 v34, v34
	s_nop 0
	v_mov_b32_e32 v36, v34
	v_exp_f32_e32 v34, v35
	s_nop 0
	v_mov_b32_e32 v37, v34
	v_pk_add_f32 v[34:35], v[212:213], v[206:207]
	s_nop 0
	v_exp_f32_e32 v34, v34
	s_nop 0
	v_mov_b32_e32 v41, v34
	v_exp_f32_e32 v34, v35
	s_nop 0
	v_mov_b32_e32 v206, v34
	v_pk_add_f32 v[34:35], v[212:213], v[46:47]
	s_nop 0
	v_exp_f32_e32 v34, v34
	s_nop 0
	v_mov_b32_e32 v46, v34
	v_exp_f32_e32 v34, v35
	s_nop 0
	v_mov_b32_e32 v207, v34
	v_pk_add_f32 v[34:35], v[212:213], v[48:49]
	s_nop 0
	v_exp_f32_e32 v34, v34
	s_nop 0
	v_mov_b32_e32 v47, v34
	v_exp_f32_e32 v34, v35
	s_nop 0
	v_mov_b32_e32 v208, v34
	v_pk_add_f32 v[34:35], v[212:213], v[44:45]
	v_cvt_pk_bf16_f32 v44, v1, v39
	v_cvt_pk_bf16_f32 v45, v36, v41
	v_cvt_pk_bf16_f32 v46, v46, v47
	s_nop 0
	v_exp_f32_e32 v34, v34
	s_nop 0
	v_mov_b32_e32 v48, v34
	v_exp_f32_e32 v34, v35
	s_nop 0
	v_mov_b32_e32 v209, v34
	v_pk_add_f32 v[34:35], v[212:213], v[54:55]
	s_nop 0
	v_exp_f32_e32 v34, v34
	s_nop 0
	v_mov_b32_e32 v49, v34
	v_exp_f32_e32 v34, v35
	v_cvt_pk_bf16_f32 v47, v48, v49
	v_cvt_pk_bf16_f32 v48, v38, v40
	v_cvt_pk_bf16_f32 v49, v37, v206
	s_nop 0
	v_mov_b32_e32 v54, v34
	v_pk_add_f32 v[34:35], v[212:213], v[50:51]
	v_cvt_pk_bf16_f32 v50, v207, v208
	v_cvt_pk_bf16_f32 v51, v209, v54
	s_nop 0
	v_exp_f32_e32 v34, v34
	s_nop 0
	v_mov_b32_e32 v55, v34
	v_exp_f32_e32 v34, v35
	s_nop 0
	v_mov_b32_e32 v210, v34
	v_pk_add_f32 v[34:35], v[212:213], v[56:57]
	s_nop 0
	v_exp_f32_e32 v34, v34
	s_nop 0
	v_mov_b32_e32 v56, v34
	v_exp_f32_e32 v34, v35
	v_cvt_pk_bf16_f32 v38, v55, v56
	s_nop 0
	v_mov_b32_e32 v57, v34
	v_pk_add_f32 v[34:35], v[212:213], v[52:53]
	s_nop 0
	v_exp_f32_e32 v34, v34
	s_nop 0
	v_mov_b32_e32 v52, v34
	v_exp_f32_e32 v34, v35
	s_nop 0
	v_mov_b32_e32 v53, v34
	v_pk_add_f32 v[34:35], v[212:213], v[192:193]
	s_nop 0
	v_exp_f32_e32 v34, v34
	s_nop 0
	v_mov_b32_e32 v192, v34
	v_exp_f32_e32 v34, v35
	v_cvt_pk_bf16_f32 v39, v52, v192
	s_nop 0
	v_mov_b32_e32 v193, v34
	v_pk_add_f32 v[34:35], v[212:213], v[190:191]
	s_nop 0
	v_exp_f32_e32 v34, v34
	s_nop 0
	v_mov_b32_e32 v190, v34
	v_exp_f32_e32 v34, v35
	s_nop 0
	v_mov_b32_e32 v191, v34
	v_pk_add_f32 v[34:35], v[212:213], v[64:65]
	s_nop 0
	v_exp_f32_e32 v34, v34
	s_nop 0
	v_mov_b32_e32 v64, v34
	v_exp_f32_e32 v34, v35
	v_cvt_pk_bf16_f32 v40, v190, v64
	s_nop 0
	v_mov_b32_e32 v65, v34
	v_pk_add_f32 v[34:35], v[212:213], v[62:63]
	s_nop 0
	v_exp_f32_e32 v34, v34
	s_nop 0
	v_mov_b32_e32 v62, v34
	v_exp_f32_e32 v34, v35
	s_nop 0
	v_mov_b32_e32 v63, v34
	v_pk_add_f32 v[34:35], v[212:213], v[60:61]
	v_readlane_b32 s20, v234, 43
	v_exp_f32_e32 v34, v34
	v_exp_f32_e32 v35, v35
	v_readlane_b32 s21, v234, 44
	v_mov_b32_e32 v60, v35
	v_cvt_pk_bf16_f32 v41, v62, v34
	v_cvt_pk_bf16_f32 v34, v210, v57
	v_cvt_pk_bf16_f32 v35, v53, v193
	v_cvt_pk_bf16_f32 v36, v191, v65
	v_cvt_pk_bf16_f32 v37, v63, v60
	s_mov_b32 s18, 0xc3200000
	v_cmp_gt_f32_e32 vcc, s18, v58
	v_cmp_gt_f32_e64 s[18:19], s18, v59
	s_waitcnt lgkmcnt(10)
	v_mfma_f32_16x16x32_bf16 v[158:161], v[218:221], v[44:47], v[158:161]
	v_mfma_f32_16x16x32_bf16 v[94:97], v[218:221], v[48:51], v[94:97]
	ds_read_b64_tr_b16 v[218:219], v173 offset:17600
	ds_read_b64_tr_b16 v[220:221], v173 offset:18688
	s_and_b64 s[18:19], vcc, s[18:19]
	v_cndmask_b32_e64 v1, 0, 1, s[18:19]
	s_waitcnt lgkmcnt(10)
	v_mfma_f32_16x16x32_bf16 v[154:157], v[222:225], v[44:47], v[154:157]
	v_mfma_f32_16x16x32_bf16 v[90:93], v[222:225], v[48:51], v[90:93]
	ds_read_b64_tr_b16 v[222:223], v173 offset:17632
	ds_read_b64_tr_b16 v[224:225], v173 offset:18720
	v_cmp_ne_u32_e32 vcc, 0, v1
	s_cmp_eq_u64 vcc, -1
	s_cselect_b64 s[18:19], -1, 0
	s_waitcnt lgkmcnt(10)
	v_mfma_f32_16x16x32_bf16 v[150:153], v[226:229], v[44:47], v[150:153]
	v_mfma_f32_16x16x32_bf16 v[86:89], v[226:229], v[48:51], v[86:89]
	ds_read_b64_tr_b16 v[226:227], v173 offset:19584
	ds_read_b64_tr_b16 v[228:229], v173 offset:20672
	s_and_b64 s[22:23], s[20:21], s[18:19]
	s_waitcnt lgkmcnt(10)
	v_mfma_f32_16x16x32_bf16 v[146:149], v[230:233], v[44:47], v[146:149]
	v_mfma_f32_16x16x32_bf16 v[82:85], v[230:233], v[48:51], v[82:85]
	ds_read_b64_tr_b16 v[230:231], v173 offset:19616
	ds_read_b64_tr_b16 v[232:233], v173 offset:20704
	s_waitcnt lgkmcnt(10)
	v_mfma_f32_16x16x32_bf16 v[142:145], v[236:239], v[44:47], v[142:145]
	v_mfma_f32_16x16x32_bf16 v[78:81], v[236:239], v[48:51], v[78:81]
	ds_read_b64_tr_b16 v[236:237], v173 offset:19648
	ds_read_b64_tr_b16 v[238:239], v173 offset:20736
	s_waitcnt lgkmcnt(10)
	v_mfma_f32_16x16x32_bf16 v[138:141], v[240:243], v[44:47], v[138:141]
	v_mfma_f32_16x16x32_bf16 v[74:77], v[240:243], v[48:51], v[74:77]
	ds_read_b64_tr_b16 v[240:241], v173 offset:19680
	ds_read_b64_tr_b16 v[242:243], v173 offset:20768
	s_waitcnt lgkmcnt(10)
; #define LAS __attribute__((address_space(3)))
; __device__ __forceinline__ void attn_phase(const Params& p, LAS unsigned char* lds, int cidx) {
;     ...
;                 for (int kk = 0; kk < 4; ++kk)
; #pragma unroll
;                     for (int n = 0; n < 4; ++n) {
;                         const bf16x8 kf = *(const LAS bf16x8*)(Kl + (16 * (fr >> 2) + 4 * n + (fr & 3)) * AT_P + 32 * kk + 8 * fq);
;                         st[0][n] = __builtin_amdgcn_mfma_f32_16x16x32_bf16(kf, qf[0][kk], st[0][n], 0, 0, 0);
;                         st[1][n] = __builtin_amdgcn_mfma_f32_16x16x32_bf16(kf, qf[1][kk], st[1][n], 0, 0, 0);
;                     }
;     ...
; #pragma unroll
;                 for (int k2 = 0; k2 < 2; ++k2)
; #pragma unroll
;                     for (int dt = 0; dt < 8; ++dt) {
;                         const LAS bf16_t* a0 = Vl + (16 * fq + 8 * k2 + (fr >> 2)) * AT_P + 16 * dt + 4 * (fr & 3);
;                         const s16x4 lo = __builtin_amdgcn_ds_read_tr16_b64_v4i16((LAS s16x4*)a0), hi = __builtin_amdgcn_ds_read_tr16_b64_v4i16((LAS s16x4*)(a0 + 4 * AT_P));
;                         const bf16x8 vf = (bf16x8){lo[0], lo[1], lo[2], lo[3], hi[0], hi[1], hi[2], hi[3]};
;                         o[0][dt] = __builtin_amdgcn_mfma_f32_16x16x32_bf16(vf, pb[0][k2], o[0][dt], 0, 0, 0);
;                         o[1][dt] = __builtin_amdgcn_mfma_f32_16x16x32_bf16(vf, pb[1][k2], o[1][dt], 0, 0, 0);
;                     }
;                 if (__builtin_amdgcn_ballot_w64(C[0] < -160.f && C[1] < -160.f) == ~0ull) { wdone = true;     if (lane == 0) misc[8 + wid] = 1; }
	v_mfma_f32_16x16x32_bf16 v[134:137], v[218:221], v[44:47], v[134:137]
	v_mfma_f32_16x16x32_bf16 v[70:73], v[218:221], v[48:51], v[70:73]
	ds_read_b64_tr_b16 v[218:219], v173 offset:19712
	ds_read_b64_tr_b16 v[220:221], v173 offset:20800
	s_waitcnt lgkmcnt(10)
	v_mfma_f32_16x16x32_bf16 v[114:117], v[222:225], v[44:47], v[114:117]
	v_mfma_f32_16x16x32_bf16 v[66:69], v[222:225], v[48:51], v[66:69]
	ds_read_b64_tr_b16 v[222:223], v173 offset:19744
	ds_read_b64_tr_b16 v[224:225], v173 offset:20832
	s_waitcnt lgkmcnt(10)
	v_mfma_f32_16x16x32_bf16 v[158:161], v[226:229], v[38:41], v[158:161]
	v_mfma_f32_16x16x32_bf16 v[94:97], v[226:229], v[34:37], v[94:97]
	ds_read_b64_tr_b16 v[226:227], v173 offset:19776
	ds_read_b64_tr_b16 v[228:229], v173 offset:20864
	s_waitcnt lgkmcnt(10)
	v_mfma_f32_16x16x32_bf16 v[154:157], v[230:233], v[38:41], v[154:157]
	v_mfma_f32_16x16x32_bf16 v[90:93], v[230:233], v[34:37], v[90:93]
	ds_read_b64_tr_b16 v[230:231], v173 offset:19808
	ds_read_b64_tr_b16 v[232:233], v173 offset:20896
	s_waitcnt lgkmcnt(10)
	v_mfma_f32_16x16x32_bf16 v[150:153], v[236:239], v[38:41], v[150:153]
	v_mfma_f32_16x16x32_bf16 v[86:89], v[236:239], v[34:37], v[86:89]
	s_waitcnt lgkmcnt(8)
	v_mfma_f32_16x16x32_bf16 v[146:149], v[240:243], v[38:41], v[146:149]
	v_mfma_f32_16x16x32_bf16 v[82:85], v[240:243], v[34:37], v[82:85]
	s_waitcnt lgkmcnt(6)
	v_mfma_f32_16x16x32_bf16 v[142:145], v[218:221], v[38:41], v[142:145]
	v_mfma_f32_16x16x32_bf16 v[78:81], v[218:221], v[34:37], v[78:81]
	s_waitcnt lgkmcnt(4)
	v_mfma_f32_16x16x32_bf16 v[138:141], v[222:225], v[38:41], v[138:141]
	v_mfma_f32_16x16x32_bf16 v[74:77], v[222:225], v[34:37], v[74:77]
	s_waitcnt lgkmcnt(2)
	v_mfma_f32_16x16x32_bf16 v[134:137], v[226:229], v[38:41], v[134:137]
	v_mfma_f32_16x16x32_bf16 v[70:73], v[226:229], v[34:37], v[70:73]
	s_waitcnt lgkmcnt(0)
	v_mfma_f32_16x16x32_bf16 v[114:117], v[230:233], v[38:41], v[114:117]
	v_mfma_f32_16x16x32_bf16 v[66:69], v[230:233], v[34:37], v[66:69]
	s_and_saveexec_b64 s[20:21], s[22:23]
	s_cbranch_execz .LBB0_678
	v_readlane_b32 s22, v234, 45
	s_or_b64 s[18:19], s[18:19], exec
	s_nop 0
	v_mov_b32_e32 v1, s22
	ds_write_b32 v1, v200 offset:34848
	s_branch .LBB0_678
.Latt_masked:
	ds_read_b128 v[218:221], v171
	ds_read_b128 v[222:225], v171 offset:1088
	ds_read_b128 v[226:229], v171 offset:2176
	ds_read_b128 v[230:233], v171 offset:3264
	ds_read_b128 v[236:239], v171 offset:64
	ds_read_b128 v[240:243], v171 offset:1152
	ds_read_b128 v[244:247], v171 offset:2240
	ds_read_b128 v[248:251], v171 offset:3328
	v_or_b32_e32 v1, s20, v162
	v_cmp_lt_i32_e64 s[80:81], v1, v204
	v_cmp_lt_i32_e64 s[82:83], v1, v205
	s_waitcnt lgkmcnt(7)
	v_mfma_f32_16x16x32_bf16 v[34:37], v[218:221], v[98:101], 0
	v_mfma_f32_16x16x32_bf16 v[38:41], v[218:221], v[118:121], 0
	ds_read_b128 v[218:221], v171 offset:128
	s_waitcnt lgkmcnt(7)
	v_mfma_f32_16x16x32_bf16 v[42:45], v[222:225], v[98:101], 0
	v_mfma_f32_16x16x32_bf16 v[46:49], v[222:225], v[118:121], 0
	ds_read_b128 v[222:225], v171 offset:1216
	s_waitcnt lgkmcnt(7)
	v_mfma_f32_16x16x32_bf16 v[50:53], v[226:229], v[98:101], 0
	v_mfma_f32_16x16x32_bf16 v[54:57], v[226:229], v[118:121], 0
	ds_read_b128 v[226:229], v171 offset:2304
	s_waitcnt lgkmcnt(7)
	v_mfma_f32_16x16x32_bf16 v[190:193], v[230:233], v[98:101], 0
	v_mfma_f32_16x16x32_bf16 v[206:209], v[230:233], v[118:121], 0
	ds_read_b128 v[230:233], v171 offset:3392
	s_waitcnt lgkmcnt(7)
	v_mfma_f32_16x16x32_bf16 v[34:37], v[236:239], v[102:105], v[34:37]
	v_mfma_f32_16x16x32_bf16 v[38:41], v[236:239], v[122:125], v[38:41]
	ds_read_b128 v[236:239], v171 offset:192
	s_waitcnt lgkmcnt(7)
	v_mfma_f32_16x16x32_bf16 v[42:45], v[240:243], v[102:105], v[42:45]
	v_mfma_f32_16x16x32_bf16 v[46:49], v[240:243], v[122:125], v[46:49]
	ds_read_b128 v[240:243], v171 offset:1280
	s_waitcnt lgkmcnt(7)
	v_mfma_f32_16x16x32_bf16 v[50:53], v[244:247], v[102:105], v[50:53]
	v_mfma_f32_16x16x32_bf16 v[54:57], v[244:247], v[122:125], v[54:57]
	ds_read_b128 v[244:247], v171 offset:2368
	s_waitcnt lgkmcnt(7)
	v_mfma_f32_16x16x32_bf16 v[190:193], v[248:251], v[102:105], v[190:193]
	v_mfma_f32_16x16x32_bf16 v[206:209], v[248:251], v[122:125], v[206:209]
	ds_read_b128 v[248:251], v171 offset:3456
	s_waitcnt lgkmcnt(7)
	v_mfma_f32_16x16x32_bf16 v[34:37], v[218:221], v[106:109], v[34:37]
	v_mfma_f32_16x16x32_bf16 v[38:41], v[218:221], v[126:129], v[38:41]
	s_waitcnt lgkmcnt(6)
	v_mfma_f32_16x16x32_bf16 v[42:45], v[222:225], v[106:109], v[42:45]
	v_mfma_f32_16x16x32_bf16 v[46:49], v[222:225], v[126:129], v[46:49]
	s_waitcnt lgkmcnt(5)
	v_mfma_f32_16x16x32_bf16 v[50:53], v[226:229], v[106:109], v[50:53]
	v_mfma_f32_16x16x32_bf16 v[54:57], v[226:229], v[126:129], v[54:57]
	s_waitcnt lgkmcnt(4)
	v_mfma_f32_16x16x32_bf16 v[190:193], v[230:233], v[106:109], v[190:193]
	v_mfma_f32_16x16x32_bf16 v[206:209], v[230:233], v[126:129], v[206:209]
	s_waitcnt lgkmcnt(3)
	v_mfma_f32_16x16x32_bf16 v[34:37], v[236:239], v[110:113], v[34:37]
	v_mfma_f32_16x16x32_bf16 v[38:41], v[236:239], v[130:133], v[38:41]
	s_waitcnt lgkmcnt(2)
	v_mfma_f32_16x16x32_bf16 v[42:45], v[240:243], v[110:113], v[42:45]
	v_mfma_f32_16x16x32_bf16 v[46:49], v[240:243], v[130:133], v[46:49]
	s_waitcnt lgkmcnt(1)
	v_mfma_f32_16x16x32_bf16 v[50:53], v[244:247], v[110:113], v[50:53]
	v_mfma_f32_16x16x32_bf16 v[54:57], v[244:247], v[130:133], v[54:57]
	s_waitcnt lgkmcnt(0)
; #define LAS __attribute__((address_space(3)))
; __device__ __forceinline__ void attn_phase(const Params& p, LAS unsigned char* lds, int cidx) {
;     ...
;                     const int s0 = kt * 64 + 16 * fq, tq0 = tpos0 + fr, tq1 = tpos0 + 16 + fr;
;                     f32x2 run = (f32x2){0.f, 0.f};
; #pragma unroll
;     ...
;                         const f32x2 xv = (f32x2){st[0][idx >> 2][idx & 3], st[1][idx >> 2][idx & 3]};
;                         const f32x2 ax = __builtin_elementwise_abs(xv);
;                         f32x2 e; e.x = __builtin_amdgcn_exp2f(-ax.x); e.y = __builtin_amdgcn_exp2f(-ax.y);
;                         const f32x2 e1 = e + 1.0f;
;                         f32x2 lg; lg.x = __builtin_amdgcn_logf(e1.x); lg.y = __builtin_amdgcn_logf(e1.y);
;                         const f32x2 sp = __builtin_elementwise_max(xv, (f32x2){0.f, 0.f}) + lg;
;                         const f32x2 lw = (xv - sp) + run;
;                         st[0][idx >> 2][idx & 3] = lw.x; st[1][idx >> 2][idx & 3] = lw.y;
;                         f32x2 dec; dec.x = (s0 + idx) < tq0 ? sp.x : 0.f; dec.y = (s0 + idx) < tq1 ? sp.y : 0.f;
;                         run = run - dec;
;                     }
;     ...
;                         const LAS bf16_t* a0 = Vl + (16 * fq + 8 * k2 + (fr >> 2)) * AT_P + 16 * dt + 4 * (fr & 3);
;                         const s16x4 lo = __builtin_amdgcn_ds_read_tr16_b64_v4i16((LAS s16x4*)a0), hi = __builtin_amdgcn_ds_read_tr16_b64_v4i16((LAS s16x4*)(a0 + 4 * AT_P));
	v_mfma_f32_16x16x32_bf16 v[190:193], v[248:251], v[110:113], v[190:193]
	v_mfma_f32_16x16x32_bf16 v[206:209], v[248:251], v[130:133], v[206:209]
	ds_read_b64_tr_b16 v[218:219], v173 offset:17408
	ds_read_b64_tr_b16 v[220:221], v173 offset:18496
	ds_read_b64_tr_b16 v[222:223], v173 offset:17440
	ds_read_b64_tr_b16 v[224:225], v173 offset:18528
	ds_read_b64_tr_b16 v[226:227], v173 offset:17472
	ds_read_b64_tr_b16 v[228:229], v173 offset:18560
	ds_read_b64_tr_b16 v[230:231], v173 offset:17504
	ds_read_b64_tr_b16 v[232:233], v173 offset:18592
	ds_read_b64_tr_b16 v[236:237], v173 offset:17536
	ds_read_b64_tr_b16 v[238:239], v173 offset:18624
	ds_read_b64_tr_b16 v[240:241], v173 offset:17568
	ds_read_b64_tr_b16 v[242:243], v173 offset:18656
	s_nop 6
	v_exp_f32_e64 v62, -|v193|
	v_mov_b32_e32 v60, v193
	v_exp_f32_e64 v63, -|v209|
	v_max_f32_e32 v65, 0, v209
	v_pk_add_f32 v[62:63], v[62:63], 1.0 op_sel_hi:[1,0]
	v_max_f32_e32 v64, 0, v193
	v_log_f32_e32 v62, v62
	v_log_f32_e32 v63, v63
	v_mov_b32_e32 v61, v209
	v_mov_b32_e32 v193, v208
	v_pk_add_f32 v[62:63], v[64:65], v[62:63]
	v_or_b32_e32 v64, 15, v1
	v_cmp_lt_i32_e64 s[18:19], v64, v204
	v_cmp_lt_i32_e32 vcc, v64, v205
	v_pk_add_f32 v[60:61], v[60:61], v[62:63] neg_lo:[0,1] neg_hi:[0,1]
	v_cndmask_b32_e64 v62, 0, v62, s[18:19]
	v_cndmask_b32_e32 v63, 0, v63, vcc
	v_pk_add_f32 v[64:65], v[62:63], 0 op_sel_hi:[1,0] neg_lo:[1,0] neg_hi:[1,0]
	v_exp_f32_e64 v62, -|v192|
	v_exp_f32_e64 v63, -|v208|
	v_max_f32_e32 v209, 0, v208
	v_pk_add_f32 v[62:63], v[62:63], 1.0 op_sel_hi:[1,0]
	v_max_f32_e32 v208, 0, v192
	v_log_f32_e32 v62, v62
	v_log_f32_e32 v63, v63
	v_pk_add_f32 v[60:61], v[60:61], 0 op_sel_hi:[1,0]
	v_pk_add_f32 v[208:209], v[208:209], v[62:63]
	s_nop 0
	v_pk_add_f32 v[62:63], v[192:193], v[208:209] neg_lo:[0,1] neg_hi:[0,1]
	v_or_b32_e32 v193, 14, v1
	v_cmp_lt_i32_e64 s[22:23], v193, v204
	v_cmp_lt_i32_e64 s[20:21], v193, v205
	v_pk_add_f32 v[62:63], v[62:63], v[64:65]
	v_cndmask_b32_e64 v192, 0, v208, s[22:23]
	v_cndmask_b32_e64 v193, 0, v209, s[20:21]
	v_exp_f32_e64 v208, -|v191|
	v_exp_f32_e64 v209, -|v207|
	v_pk_add_f32 v[192:193], v[64:65], v[192:193] neg_lo:[0,1] neg_hi:[0,1]
	v_mov_b32_e32 v64, v191
	v_mov_b32_e32 v65, v207
	v_pk_add_f32 v[208:209], v[208:209], 1.0 op_sel_hi:[1,0]
	v_log_f32_e32 v208, v208
	v_log_f32_e32 v209, v209
	v_max_f32_e32 v211, 0, v207
	v_max_f32_e32 v210, 0, v191
	v_or_b32_e32 v191, 13, v1
	v_pk_add_f32 v[208:209], v[210:211], v[208:209]
	v_cmp_lt_i32_e64 s[26:27], v191, v204
	v_cmp_lt_i32_e64 s[24:25], v191, v205
	v_pk_add_f32 v[64:65], v[64:65], v[208:209] neg_lo:[0,1] neg_hi:[0,1]
	v_cndmask_b32_e64 v208, 0, v208, s[26:27]
	v_cndmask_b32_e64 v209, 0, v209, s[24:25]
	v_pk_add_f32 v[64:65], v[64:65], v[192:193]
	v_pk_add_f32 v[192:193], v[192:193], v[208:209] neg_lo:[0,1] neg_hi:[0,1]
	v_exp_f32_e64 v208, -|v190|
	v_exp_f32_e64 v209, -|v206|
	v_mov_b32_e32 v191, v206
	v_max_f32_e32 v207, 0, v206
	v_pk_add_f32 v[208:209], v[208:209], 1.0 op_sel_hi:[1,0]
	v_log_f32_e32 v208, v208
	v_log_f32_e32 v209, v209
	v_max_f32_e32 v206, 0, v190
	v_pk_add_f32 v[206:207], v[206:207], v[208:209]
	v_or_b32_e32 v208, 12, v1
	v_cmp_lt_i32_e64 s[28:29], v208, v204
	v_cmp_lt_i32_e64 s[30:31], v208, v205
	v_exp_f32_e64 v208, -|v53|
	v_exp_f32_e64 v209, -|v57|
	v_pk_add_f32 v[190:191], v[190:191], v[206:207] neg_lo:[0,1] neg_hi:[0,1]
	v_cndmask_b32_e64 v206, 0, v206, s[28:29]
	v_cndmask_b32_e64 v207, 0, v207, s[30:31]
	v_pk_add_f32 v[208:209], v[208:209], 1.0 op_sel_hi:[1,0]
	v_pk_add_f32 v[190:191], v[190:191], v[192:193]
	v_log_f32_e32 v208, v208
	v_log_f32_e32 v209, v209
	v_pk_add_f32 v[206:207], v[192:193], v[206:207] neg_lo:[0,1] neg_hi:[0,1]
	v_mov_b32_e32 v192, v53
	v_mov_b32_e32 v193, v57
	v_max_f32_e32 v211, 0, v57
	v_max_f32_e32 v210, 0, v53
	v_or_b32_e32 v53, 11, v1
	v_pk_add_f32 v[208:209], v[210:211], v[208:209]
	v_cmp_lt_i32_e64 s[36:37], v53, v204
	v_cmp_lt_i32_e64 s[34:35], v53, v205
	v_pk_add_f32 v[192:193], v[192:193], v[208:209] neg_lo:[0,1] neg_hi:[0,1]
	v_cndmask_b32_e64 v208, 0, v208, s[36:37]
	v_cndmask_b32_e64 v209, 0, v209, s[34:35]
	v_pk_add_f32 v[192:193], v[192:193], v[206:207]
	v_pk_add_f32 v[206:207], v[206:207], v[208:209] neg_lo:[0,1] neg_hi:[0,1]
	v_exp_f32_e64 v208, -|v52|
	v_exp_f32_e64 v209, -|v56|
	v_mov_b32_e32 v53, v56
	v_max_f32_e32 v57, 0, v56
	v_pk_add_f32 v[208:209], v[208:209], 1.0 op_sel_hi:[1,0]
	v_log_f32_e32 v208, v208
	v_log_f32_e32 v209, v209
	v_max_f32_e32 v56, 0, v52
	v_pk_add_f32 v[56:57], v[56:57], v[208:209]
	v_or_b32_e32 v208, 10, v1
	v_cmp_lt_i32_e64 s[40:41], v208, v204
	v_cmp_lt_i32_e64 s[38:39], v208, v205
	v_exp_f32_e64 v208, -|v51|
	v_exp_f32_e64 v209, -|v55|
	v_pk_add_f32 v[52:53], v[52:53], v[56:57] neg_lo:[0,1] neg_hi:[0,1]
	v_cndmask_b32_e64 v56, 0, v56, s[40:41]
	v_cndmask_b32_e64 v57, 0, v57, s[38:39]
	v_pk_add_f32 v[208:209], v[208:209], 1.0 op_sel_hi:[1,0]
	v_pk_add_f32 v[52:53], v[52:53], v[206:207]
	v_log_f32_e32 v208, v208
	v_log_f32_e32 v209, v209
	v_pk_add_f32 v[206:207], v[206:207], v[56:57] neg_lo:[0,1] neg_hi:[0,1]
	v_mov_b32_e32 v56, v51
	v_mov_b32_e32 v57, v55
	v_max_f32_e32 v211, 0, v55
	v_max_f32_e32 v210, 0, v51
	v_or_b32_e32 v51, 9, v1
	v_pk_add_f32 v[208:209], v[210:211], v[208:209]
	v_cmp_lt_i32_e64 s[44:45], v51, v204
	v_cmp_lt_i32_e64 s[42:43], v51, v205
	v_pk_add_f32 v[56:57], v[56:57], v[208:209] neg_lo:[0,1] neg_hi:[0,1]
	v_cndmask_b32_e64 v208, 0, v208, s[44:45]
	v_cndmask_b32_e64 v209, 0, v209, s[42:43]
	v_pk_add_f32 v[56:57], v[56:57], v[206:207]
	v_pk_add_f32 v[206:207], v[206:207], v[208:209] neg_lo:[0,1] neg_hi:[0,1]
	v_exp_f32_e64 v208, -|v50|
	v_exp_f32_e64 v209, -|v54|
; __device__ __forceinline__ void attn_phase(const Params& p, LAS unsigned char* lds, int cidx) {
;     ...
;                         const f32x2 xv = (f32x2){st[0][idx >> 2][idx & 3], st[1][idx >> 2][idx & 3]};
;                         const f32x2 ax = __builtin_elementwise_abs(xv);
;                         f32x2 e; e.x = __builtin_amdgcn_exp2f(-ax.x); e.y = __builtin_amdgcn_exp2f(-ax.y);
;                         const f32x2 e1 = e + 1.0f;
;                         f32x2 lg; lg.x = __builtin_amdgcn_logf(e1.x); lg.y = __builtin_amdgcn_logf(e1.y);
;                         const f32x2 sp = __builtin_elementwise_max(xv, (f32x2){0.f, 0.f}) + lg;
;                         const f32x2 lw = (xv - sp) + run;
;                         st[0][idx >> 2][idx & 3] = lw.x; st[1][idx >> 2][idx & 3] = lw.y;
;                         f32x2 dec; dec.x = (s0 + idx) < tq0 ? sp.x : 0.f; dec.y = (s0 + idx) < tq1 ? sp.y : 0.f;
;                         run = run - dec;
;                     }
;                     f32x2 t16, t32, t48;
;                     t16.x = __shfl(run.x, (lane + 16) & 63); t16.y = __shfl(run.y, (lane + 16) & 63);
;                     t32.x = __shfl(run.x, (lane + 32) & 63); t32.y = __shfl(run.y, (lane + 32) & 63);
;                     t48.x = __shfl(run.x, (lane + 48) & 63); t48.y = __shfl(run.y, (lane + 48) & 63);
	v_mov_b32_e32 v51, v54
	v_max_f32_e32 v55, 0, v54
	v_pk_add_f32 v[208:209], v[208:209], 1.0 op_sel_hi:[1,0]
	v_log_f32_e32 v208, v208
	v_log_f32_e32 v209, v209
	v_max_f32_e32 v54, 0, v50
	v_pk_add_f32 v[54:55], v[54:55], v[208:209]
	v_or_b32_e32 v208, 8, v1
	v_cmp_lt_i32_e64 s[48:49], v208, v204
	v_cmp_lt_i32_e64 s[46:47], v208, v205
	v_exp_f32_e64 v208, -|v45|
	v_exp_f32_e64 v209, -|v49|
	v_pk_add_f32 v[50:51], v[50:51], v[54:55] neg_lo:[0,1] neg_hi:[0,1]
	v_cndmask_b32_e64 v54, 0, v54, s[48:49]
	v_cndmask_b32_e64 v55, 0, v55, s[46:47]
	v_pk_add_f32 v[208:209], v[208:209], 1.0 op_sel_hi:[1,0]
	v_pk_add_f32 v[50:51], v[50:51], v[206:207]
	v_log_f32_e32 v208, v208
	v_log_f32_e32 v209, v209
	v_pk_add_f32 v[206:207], v[206:207], v[54:55] neg_lo:[0,1] neg_hi:[0,1]
	v_mov_b32_e32 v54, v45
	v_mov_b32_e32 v55, v49
	v_max_f32_e32 v211, 0, v49
	v_max_f32_e32 v210, 0, v45
	v_or_b32_e32 v45, 7, v1
	v_pk_add_f32 v[208:209], v[210:211], v[208:209]
	v_cmp_lt_i32_e64 s[52:53], v45, v204
	v_cmp_lt_i32_e64 s[50:51], v45, v205
	v_pk_add_f32 v[54:55], v[54:55], v[208:209] neg_lo:[0,1] neg_hi:[0,1]
	v_cndmask_b32_e64 v208, 0, v208, s[52:53]
	v_cndmask_b32_e64 v209, 0, v209, s[50:51]
	v_pk_add_f32 v[54:55], v[54:55], v[206:207]
	v_pk_add_f32 v[206:207], v[206:207], v[208:209] neg_lo:[0,1] neg_hi:[0,1]
	v_exp_f32_e64 v208, -|v44|
	v_exp_f32_e64 v209, -|v48|
	v_mov_b32_e32 v45, v48
	v_max_f32_e32 v49, 0, v48
	v_pk_add_f32 v[208:209], v[208:209], 1.0 op_sel_hi:[1,0]
	v_log_f32_e32 v208, v208
	v_log_f32_e32 v209, v209
	v_max_f32_e32 v48, 0, v44
	v_pk_add_f32 v[48:49], v[48:49], v[208:209]
	v_or_b32_e32 v208, 6, v1
	v_cmp_lt_i32_e64 s[56:57], v208, v204
	v_cmp_lt_i32_e64 s[54:55], v208, v205
	v_exp_f32_e64 v208, -|v43|
	v_exp_f32_e64 v209, -|v47|
	v_pk_add_f32 v[44:45], v[44:45], v[48:49] neg_lo:[0,1] neg_hi:[0,1]
	v_cndmask_b32_e64 v48, 0, v48, s[56:57]
	v_cndmask_b32_e64 v49, 0, v49, s[54:55]
	v_pk_add_f32 v[208:209], v[208:209], 1.0 op_sel_hi:[1,0]
	v_pk_add_f32 v[44:45], v[44:45], v[206:207]
	v_log_f32_e32 v208, v208
	v_log_f32_e32 v209, v209
	v_pk_add_f32 v[206:207], v[206:207], v[48:49] neg_lo:[0,1] neg_hi:[0,1]
	v_mov_b32_e32 v48, v43
	v_mov_b32_e32 v49, v47
	v_max_f32_e32 v211, 0, v47
	v_max_f32_e32 v210, 0, v43
	v_or_b32_e32 v43, 5, v1
	v_pk_add_f32 v[208:209], v[210:211], v[208:209]
	v_cmp_lt_i32_e64 s[60:61], v43, v204
	v_cmp_lt_i32_e64 s[58:59], v43, v205
	v_pk_add_f32 v[48:49], v[48:49], v[208:209] neg_lo:[0,1] neg_hi:[0,1]
	v_cndmask_b32_e64 v208, 0, v208, s[60:61]
	v_cndmask_b32_e64 v209, 0, v209, s[58:59]
	v_pk_add_f32 v[48:49], v[48:49], v[206:207]
	v_pk_add_f32 v[206:207], v[206:207], v[208:209] neg_lo:[0,1] neg_hi:[0,1]
	v_exp_f32_e64 v208, -|v42|
	v_exp_f32_e64 v209, -|v46|
	v_mov_b32_e32 v43, v46
	v_max_f32_e32 v47, 0, v46
	v_pk_add_f32 v[208:209], v[208:209], 1.0 op_sel_hi:[1,0]
	v_log_f32_e32 v208, v208
	v_log_f32_e32 v209, v209
	v_max_f32_e32 v46, 0, v42
	v_pk_add_f32 v[208:209], v[46:47], v[208:209]
	s_nop 0
	v_pk_add_f32 v[42:43], v[42:43], v[208:209] neg_lo:[0,1] neg_hi:[0,1]
	s_nop 0
	v_pk_add_f32 v[46:47], v[42:43], v[206:207]
	v_or_b32_e32 v43, 4, v1
	v_cmp_lt_i32_e64 s[64:65], v43, v204
	v_cmp_lt_i32_e64 s[62:63], v43, v205
	s_nop 0
	v_cndmask_b32_e64 v42, 0, v208, s[64:65]
	v_cndmask_b32_e64 v43, 0, v209, s[62:63]
	v_exp_f32_e64 v208, -|v37|
	v_exp_f32_e64 v209, -|v41|
	v_pk_add_f32 v[42:43], v[206:207], v[42:43] neg_lo:[0,1] neg_hi:[0,1]
	v_mov_b32_e32 v206, v37
	v_mov_b32_e32 v207, v41
	v_pk_add_f32 v[208:209], v[208:209], 1.0 op_sel_hi:[1,0]
	v_log_f32_e32 v208, v208
	v_log_f32_e32 v209, v209
	v_max_f32_e32 v211, 0, v41
	v_max_f32_e32 v210, 0, v37
	v_or_b32_e32 v37, 3, v1
	v_pk_add_f32 v[208:209], v[210:211], v[208:209]
	v_cmp_lt_i32_e64 s[68:69], v37, v204
	v_cmp_lt_i32_e64 s[66:67], v37, v205
	v_pk_add_f32 v[206:207], v[206:207], v[208:209] neg_lo:[0,1] neg_hi:[0,1]
	v_cndmask_b32_e64 v208, 0, v208, s[68:69]
	v_cndmask_b32_e64 v209, 0, v209, s[66:67]
	v_pk_add_f32 v[206:207], v[206:207], v[42:43]
	v_pk_add_f32 v[42:43], v[42:43], v[208:209] neg_lo:[0,1] neg_hi:[0,1]
	v_exp_f32_e64 v208, -|v36|
	v_exp_f32_e64 v209, -|v40|
	v_mov_b32_e32 v37, v40
	v_max_f32_e32 v41, 0, v40
	v_pk_add_f32 v[208:209], v[208:209], 1.0 op_sel_hi:[1,0]
	v_log_f32_e32 v208, v208
	v_log_f32_e32 v209, v209
	v_max_f32_e32 v40, 0, v36
	v_pk_add_f32 v[40:41], v[40:41], v[208:209]
	v_or_b32_e32 v208, 2, v1
	v_cmp_lt_i32_e64 s[72:73], v208, v204
	v_cmp_lt_i32_e64 s[70:71], v208, v205
	v_exp_f32_e64 v208, -|v35|
	v_exp_f32_e64 v209, -|v39|
	v_pk_add_f32 v[36:37], v[36:37], v[40:41] neg_lo:[0,1] neg_hi:[0,1]
	v_cndmask_b32_e64 v40, 0, v40, s[72:73]
	v_cndmask_b32_e64 v41, 0, v41, s[70:71]
	v_pk_add_f32 v[208:209], v[208:209], 1.0 op_sel_hi:[1,0]
	v_pk_add_f32 v[36:37], v[36:37], v[42:43]
	v_log_f32_e32 v208, v208
	v_log_f32_e32 v209, v209
	v_pk_add_f32 v[40:41], v[42:43], v[40:41] neg_lo:[0,1] neg_hi:[0,1]
	v_mov_b32_e32 v42, v35
	v_mov_b32_e32 v43, v39
	v_max_f32_e32 v211, 0, v39
	v_max_f32_e32 v210, 0, v35
	v_pk_add_f32 v[208:209], v[210:211], v[208:209]
	v_or_b32_e32 v35, 1, v1
	v_pk_add_f32 v[42:43], v[42:43], v[208:209] neg_lo:[0,1] neg_hi:[0,1]
	v_cmp_lt_i32_e64 s[76:77], v35, v204
	v_cmp_lt_i32_e64 s[74:75], v35, v205
	v_pk_add_f32 v[210:211], v[42:43], v[40:41]
	v_cndmask_b32_e64 v42, 0, v208, s[76:77]
	v_cndmask_b32_e64 v43, 0, v209, s[74:75]
	v_pk_add_f32 v[40:41], v[40:41], v[42:43] neg_lo:[0,1] neg_hi:[0,1]
	v_exp_f32_e64 v42, -|v34|
	v_exp_f32_e64 v43, -|v38|
	v_mov_b32_e32 v35, v38
	v_max_f32_e32 v39, 0, v38
	v_pk_add_f32 v[42:43], v[42:43], 1.0 op_sel_hi:[1,0]
	v_log_f32_e32 v42, v42
	v_log_f32_e32 v43, v43
	v_max_f32_e32 v38, 0, v34
	v_or_b32_e32 v1, v201, v196
	v_lshlrev_b32_e32 v1, 2, v1
	v_pk_add_f32 v[38:39], v[38:39], v[42:43]
	v_xor_b32_e32 v1, 0x80, v1
	v_pk_add_f32 v[34:35], v[34:35], v[38:39] neg_lo:[0,1] neg_hi:[0,1]
	v_cndmask_b32_e64 v38, 0, v38, s[80:81]
	v_cndmask_b32_e64 v39, 0, v39, s[82:83]
	v_pk_add_f32 v[38:39], v[40:41], v[38:39] neg_lo:[0,1] neg_hi:[0,1]
	v_pk_add_f32 v[34:35], v[34:35], v[40:41]
	ds_bpermute_b32 v40, v202, v38
	ds_bpermute_b32 v41, v202, v39
	ds_bpermute_b32 v42, v1, v38
	ds_bpermute_b32 v43, v1, v39
	ds_bpermute_b32 v208, v203, v38
	ds_bpermute_b32 v209, v203, v39
	s_waitcnt lgkmcnt(4)
; __device__ __forceinline__ unsigned cvt_pk_bf16(float lo, float hi) { unsigned r; asm volatile("v_cvt_pk_bf16_f32 %0, %1, %2" : "=v"(r) : "v"(lo), "v"(hi)); return r; }
; __device__ __forceinline__ void attn_phase(const Params& p, LAS unsigned char* lds, int cidx) {
;     ...
;                     const f32x2 higher = (fq < 3 ? t16 : z2) + (fq < 2 ? t32 : z2) + (fq < 1 ? t48 : z2);
;                     const f32x2 base = (f32x2){C[0], C[1]} + higher;
;                     const f32x2 tot = (run + t16) + (t32 + t48);
;                     C[0] += tot.x; C[1] += tot.y;
;                     float w0[16], w1[16];
; #pragma unroll
;                     for (int idx = 0; idx < 16; ++idx) {
;                         const f32x2 a2 = (f32x2){st[0][idx >> 2][idx & 3], st[1][idx >> 2][idx & 3]} + base;
;                         w0[idx] = (s0 + idx) < tq0 ? __builtin_amdgcn_exp2f(a2.x) : 0.f;
;                         w1[idx] = (s0 + idx) < tq1 ? __builtin_amdgcn_exp2f(a2.y) : 0.f;
;                     }
; #pragma unroll
;                     for (int k2 = 0; k2 < 2; ++k2) {
;                         u32x4 pw; pw.x = cvt_pk_bf16(w0[8 * k2 + 0], w0[8 * k2 + 1]); pw.y = cvt_pk_bf16(w0[8 * k2 + 2], w0[8 * k2 + 3]); pw.z = cvt_pk_bf16(w0[8 * k2 + 4], w0[8 * k2 + 5]); pw.w = cvt_pk_bf16(w0[8 * k2 + 6], w0[8 * k2 + 7]);
;                         pb[0][k2] = __builtin_bit_cast(bf16x8, pw);
;                         u32x4 pv; pv.x = cvt_pk_bf16(w1[8 * k2 + 0], w1[8 * k2 + 1]); pv.y = cvt_pk_bf16(w1[8 * k2 + 2], w1[8 * k2 + 3]); pv.z = cvt_pk_bf16(w1[8 * k2 + 4], w1[8 * k2 + 5]); pv.w = cvt_pk_bf16(w1[8 * k2 + 6], w1[8 * k2 + 7]);
;                         pb[1][k2] = __builtin_bit_cast(bf16x8, pv);
;                     }
	v_cndmask_b32_e64 v213, v41, 0, s[8:9]
	v_cndmask_b32_e64 v212, v40, 0, s[8:9]
	s_waitcnt lgkmcnt(2)
	v_cndmask_b32_e64 v215, 0, v43, s[10:11]
	v_cndmask_b32_e64 v214, 0, v42, s[10:11]
	v_pk_add_f32 v[212:213], v[212:213], v[214:215]
	s_waitcnt lgkmcnt(0)
	v_cndmask_b32_e64 v215, 0, v209, s[12:13]
	v_cndmask_b32_e64 v214, 0, v208, s[12:13]
	v_pk_add_f32 v[212:213], v[212:213], v[214:215]
	v_pk_add_f32 v[38:39], v[38:39], v[40:41]
	v_pk_add_f32 v[212:213], v[58:59], v[212:213]
	v_pk_add_f32 v[40:41], v[42:43], v[208:209]
	v_pk_add_f32 v[34:35], v[212:213], v[34:35]
	v_pk_add_f32 v[42:43], v[40:41], v[38:39]
	v_exp_f32_e32 v1, v34
	v_exp_f32_e32 v34, v35
	v_pk_add_f32 v[58:59], v[58:59], v[42:43]
	v_cndmask_b32_e64 v1, 0, v1, s[80:81]
	v_cndmask_b32_e64 v38, 0, v34, s[82:83]
	v_pk_add_f32 v[34:35], v[212:213], v[210:211]
	s_nop 0
	v_exp_f32_e32 v34, v34
	s_nop 0
	v_cndmask_b32_e64 v39, 0, v34, s[76:77]
	v_exp_f32_e32 v34, v35
	s_nop 0
	v_cndmask_b32_e64 v40, 0, v34, s[74:75]
	v_pk_add_f32 v[34:35], v[212:213], v[36:37]
	s_nop 0
	v_exp_f32_e32 v34, v34
	s_nop 0
	v_cndmask_b32_e64 v36, 0, v34, s[72:73]
	v_exp_f32_e32 v34, v35
	s_nop 0
	v_cndmask_b32_e64 v37, 0, v34, s[70:71]
	v_pk_add_f32 v[34:35], v[212:213], v[206:207]
	s_nop 0
	v_exp_f32_e32 v34, v34
	s_nop 0
	v_cndmask_b32_e64 v41, 0, v34, s[68:69]
	v_exp_f32_e32 v34, v35
	s_nop 0
	v_cndmask_b32_e64 v206, 0, v34, s[66:67]
	v_pk_add_f32 v[34:35], v[212:213], v[46:47]
	s_nop 0
	v_exp_f32_e32 v34, v34
	s_nop 0
	v_cndmask_b32_e64 v46, 0, v34, s[64:65]
	v_exp_f32_e32 v34, v35
	s_nop 0
	v_cndmask_b32_e64 v207, 0, v34, s[62:63]
	v_pk_add_f32 v[34:35], v[212:213], v[48:49]
	s_nop 0
	v_exp_f32_e32 v34, v34
	s_nop 0
	v_cndmask_b32_e64 v47, 0, v34, s[60:61]
	v_exp_f32_e32 v34, v35
	s_nop 0
	v_cndmask_b32_e64 v208, 0, v34, s[58:59]
	v_pk_add_f32 v[34:35], v[212:213], v[44:45]
	v_cvt_pk_bf16_f32 v44, v1, v39
	v_cvt_pk_bf16_f32 v45, v36, v41
	v_cvt_pk_bf16_f32 v46, v46, v47
	s_nop 0
	v_exp_f32_e32 v34, v34
	s_nop 0
	v_cndmask_b32_e64 v48, 0, v34, s[56:57]
	v_exp_f32_e32 v34, v35
	s_nop 0
	v_cndmask_b32_e64 v209, 0, v34, s[54:55]
	v_pk_add_f32 v[34:35], v[212:213], v[54:55]
	s_nop 0
	v_exp_f32_e32 v34, v34
	s_nop 0
	v_cndmask_b32_e64 v49, 0, v34, s[52:53]
	v_exp_f32_e32 v34, v35
	v_cvt_pk_bf16_f32 v47, v48, v49
	v_cvt_pk_bf16_f32 v48, v38, v40
	v_cvt_pk_bf16_f32 v49, v37, v206
	s_nop 0
	v_cndmask_b32_e64 v54, 0, v34, s[50:51]
	v_pk_add_f32 v[34:35], v[212:213], v[50:51]
	v_cvt_pk_bf16_f32 v50, v207, v208
	v_cvt_pk_bf16_f32 v51, v209, v54
	s_nop 0
	v_exp_f32_e32 v34, v34
	s_nop 0
	v_cndmask_b32_e64 v55, 0, v34, s[48:49]
	v_exp_f32_e32 v34, v35
	s_nop 0
	v_cndmask_b32_e64 v210, 0, v34, s[46:47]
	v_pk_add_f32 v[34:35], v[212:213], v[56:57]
	s_nop 0
	v_exp_f32_e32 v34, v34
	s_nop 0
	v_cndmask_b32_e64 v56, 0, v34, s[44:45]
	v_exp_f32_e32 v34, v35
	v_cvt_pk_bf16_f32 v38, v55, v56
	s_nop 0
	v_cndmask_b32_e64 v57, 0, v34, s[42:43]
	v_pk_add_f32 v[34:35], v[212:213], v[52:53]
	s_nop 0
	v_exp_f32_e32 v34, v34
	s_nop 0
	v_cndmask_b32_e64 v52, 0, v34, s[40:41]
	v_exp_f32_e32 v34, v35
	s_nop 0
	v_cndmask_b32_e64 v53, 0, v34, s[38:39]
	v_pk_add_f32 v[34:35], v[212:213], v[192:193]
	s_nop 0
	v_exp_f32_e32 v34, v34
	s_nop 0
	v_cndmask_b32_e64 v192, 0, v34, s[36:37]
	v_exp_f32_e32 v34, v35
	v_cvt_pk_bf16_f32 v39, v52, v192
	s_nop 0
	v_cndmask_b32_e64 v193, 0, v34, s[34:35]
	v_pk_add_f32 v[34:35], v[212:213], v[190:191]
	s_nop 0
	v_exp_f32_e32 v34, v34
	s_nop 0
	v_cndmask_b32_e64 v190, 0, v34, s[28:29]
	v_exp_f32_e32 v34, v35
	s_nop 0
	v_cndmask_b32_e64 v191, 0, v34, s[30:31]
	v_pk_add_f32 v[34:35], v[212:213], v[64:65]
	s_nop 0
	v_exp_f32_e32 v34, v34
	s_nop 0
	v_cndmask_b32_e64 v64, 0, v34, s[26:27]
	v_exp_f32_e32 v34, v35
	v_cvt_pk_bf16_f32 v40, v190, v64
	s_nop 0
	v_cndmask_b32_e64 v65, 0, v34, s[24:25]
	v_pk_add_f32 v[34:35], v[212:213], v[62:63]
	s_nop 0
	v_exp_f32_e32 v34, v34
	s_nop 0
	v_cndmask_b32_e64 v62, 0, v34, s[22:23]
	v_exp_f32_e32 v34, v35
	s_nop 0
	v_cndmask_b32_e64 v63, 0, v34, s[20:21]
	v_pk_add_f32 v[34:35], v[212:213], v[60:61]
	v_readlane_b32 s20, v234, 43
	v_exp_f32_e32 v34, v34
	v_exp_f32_e32 v35, v35
	v_readlane_b32 s21, v234, 44
	v_cndmask_b32_e64 v34, 0, v34, s[18:19]
	v_cndmask_b32_e32 v60, 0, v35, vcc
	v_cvt_pk_bf16_f32 v41, v62, v34
	v_cvt_pk_bf16_f32 v34, v210, v57
	v_cvt_pk_bf16_f32 v35, v53, v193
	v_cvt_pk_bf16_f32 v36, v191, v65
	v_cvt_pk_bf16_f32 v37, v63, v60
	s_mov_b32 s18, 0xc3200000
	v_cmp_gt_f32_e32 vcc, s18, v58
	v_cmp_gt_f32_e64 s[18:19], s18, v59
	s_waitcnt lgkmcnt(10)
; #define LAS __attribute__((address_space(3)))
; __device__ __forceinline__ void attn_phase(const Params& p, LAS unsigned char* lds, int cidx) {
;     ...
; #pragma unroll
;                 for (int k2 = 0; k2 < 2; ++k2)
; #pragma unroll
;                     for (int dt = 0; dt < 8; ++dt) {
;                         const LAS bf16_t* a0 = Vl + (16 * fq + 8 * k2 + (fr >> 2)) * AT_P + 16 * dt + 4 * (fr & 3);
;                         const s16x4 lo = __builtin_amdgcn_ds_read_tr16_b64_v4i16((LAS s16x4*)a0), hi = __builtin_amdgcn_ds_read_tr16_b64_v4i16((LAS s16x4*)(a0 + 4 * AT_P));
;                         const bf16x8 vf = (bf16x8){lo[0], lo[1], lo[2], lo[3], hi[0], hi[1], hi[2], hi[3]};
;                         o[0][dt] = __builtin_amdgcn_mfma_f32_16x16x32_bf16(vf, pb[0][k2], o[0][dt], 0, 0, 0);
;                         o[1][dt] = __builtin_amdgcn_mfma_f32_16x16x32_bf16(vf, pb[1][k2], o[1][dt], 0, 0, 0);
;                     }
;                 if (__builtin_amdgcn_ballot_w64(C[0] < -160.f && C[1] < -160.f) == ~0ull) { wdone = true;     if (lane == 0) misc[8 + wid] = 1; }
	v_mfma_f32_16x16x32_bf16 v[158:161], v[218:221], v[44:47], v[158:161]
	v_mfma_f32_16x16x32_bf16 v[94:97], v[218:221], v[48:51], v[94:97]
	ds_read_b64_tr_b16 v[218:219], v173 offset:17600
	ds_read_b64_tr_b16 v[220:221], v173 offset:18688
	s_and_b64 s[18:19], vcc, s[18:19]
	v_cndmask_b32_e64 v1, 0, 1, s[18:19]
	s_waitcnt lgkmcnt(10)
	v_mfma_f32_16x16x32_bf16 v[154:157], v[222:225], v[44:47], v[154:157]
	v_mfma_f32_16x16x32_bf16 v[90:93], v[222:225], v[48:51], v[90:93]
	ds_read_b64_tr_b16 v[222:223], v173 offset:17632
	ds_read_b64_tr_b16 v[224:225], v173 offset:18720
	v_cmp_ne_u32_e32 vcc, 0, v1
	s_cmp_eq_u64 vcc, -1
	s_cselect_b64 s[18:19], -1, 0
	s_waitcnt lgkmcnt(10)
	v_mfma_f32_16x16x32_bf16 v[150:153], v[226:229], v[44:47], v[150:153]
	v_mfma_f32_16x16x32_bf16 v[86:89], v[226:229], v[48:51], v[86:89]
	ds_read_b64_tr_b16 v[226:227], v173 offset:19584
	ds_read_b64_tr_b16 v[228:229], v173 offset:20672
	s_and_b64 s[22:23], s[20:21], s[18:19]
	s_waitcnt lgkmcnt(10)
	v_mfma_f32_16x16x32_bf16 v[146:149], v[230:233], v[44:47], v[146:149]
	v_mfma_f32_16x16x32_bf16 v[82:85], v[230:233], v[48:51], v[82:85]
	ds_read_b64_tr_b16 v[230:231], v173 offset:19616
	ds_read_b64_tr_b16 v[232:233], v173 offset:20704
	s_waitcnt lgkmcnt(10)
	v_mfma_f32_16x16x32_bf16 v[142:145], v[236:239], v[44:47], v[142:145]
	v_mfma_f32_16x16x32_bf16 v[78:81], v[236:239], v[48:51], v[78:81]
	ds_read_b64_tr_b16 v[236:237], v173 offset:19648
	ds_read_b64_tr_b16 v[238:239], v173 offset:20736
	s_waitcnt lgkmcnt(10)
	v_mfma_f32_16x16x32_bf16 v[138:141], v[240:243], v[44:47], v[138:141]
	v_mfma_f32_16x16x32_bf16 v[74:77], v[240:243], v[48:51], v[74:77]
	ds_read_b64_tr_b16 v[240:241], v173 offset:19680
	ds_read_b64_tr_b16 v[242:243], v173 offset:20768
	s_waitcnt lgkmcnt(10)
	v_mfma_f32_16x16x32_bf16 v[134:137], v[218:221], v[44:47], v[134:137]
	v_mfma_f32_16x16x32_bf16 v[70:73], v[218:221], v[48:51], v[70:73]
	ds_read_b64_tr_b16 v[218:219], v173 offset:19712
	ds_read_b64_tr_b16 v[220:221], v173 offset:20800
	s_waitcnt lgkmcnt(10)
	v_mfma_f32_16x16x32_bf16 v[114:117], v[222:225], v[44:47], v[114:117]
	v_mfma_f32_16x16x32_bf16 v[66:69], v[222:225], v[48:51], v[66:69]
	ds_read_b64_tr_b16 v[222:223], v173 offset:19744
	ds_read_b64_tr_b16 v[224:225], v173 offset:20832
	s_waitcnt lgkmcnt(10)
	v_mfma_f32_16x16x32_bf16 v[158:161], v[226:229], v[38:41], v[158:161]
	v_mfma_f32_16x16x32_bf16 v[94:97], v[226:229], v[34:37], v[94:97]
	ds_read_b64_tr_b16 v[226:227], v173 offset:19776
	ds_read_b64_tr_b16 v[228:229], v173 offset:20864
	s_waitcnt lgkmcnt(10)
	v_mfma_f32_16x16x32_bf16 v[154:157], v[230:233], v[38:41], v[154:157]
	v_mfma_f32_16x16x32_bf16 v[90:93], v[230:233], v[34:37], v[90:93]
	ds_read_b64_tr_b16 v[230:231], v173 offset:19808
	ds_read_b64_tr_b16 v[232:233], v173 offset:20896
	s_waitcnt lgkmcnt(10)
	v_mfma_f32_16x16x32_bf16 v[150:153], v[236:239], v[38:41], v[150:153]
	v_mfma_f32_16x16x32_bf16 v[86:89], v[236:239], v[34:37], v[86:89]
	s_waitcnt lgkmcnt(8)
	v_mfma_f32_16x16x32_bf16 v[146:149], v[240:243], v[38:41], v[146:149]
	v_mfma_f32_16x16x32_bf16 v[82:85], v[240:243], v[34:37], v[82:85]
	s_waitcnt lgkmcnt(6)
	v_mfma_f32_16x16x32_bf16 v[142:145], v[218:221], v[38:41], v[142:145]
	v_mfma_f32_16x16x32_bf16 v[78:81], v[218:221], v[34:37], v[78:81]
	s_waitcnt lgkmcnt(4)
	v_mfma_f32_16x16x32_bf16 v[138:141], v[222:225], v[38:41], v[138:141]
	v_mfma_f32_16x16x32_bf16 v[74:77], v[222:225], v[34:37], v[74:77]
	s_waitcnt lgkmcnt(2)
	v_mfma_f32_16x16x32_bf16 v[134:137], v[226:229], v[38:41], v[134:137]
	v_mfma_f32_16x16x32_bf16 v[70:73], v[226:229], v[34:37], v[70:73]
	s_waitcnt lgkmcnt(0)
	v_mfma_f32_16x16x32_bf16 v[114:117], v[230:233], v[38:41], v[114:117]
	v_mfma_f32_16x16x32_bf16 v[66:69], v[230:233], v[34:37], v[66:69]
	s_and_saveexec_b64 s[20:21], s[22:23]
	s_cbranch_execz .LBB0_678
	v_readlane_b32 s22, v234, 45
	s_or_b64 s[18:19], s[18:19], exec
	s_nop 0
	v_mov_b32_e32 v1, s22
	ds_write_b32 v1, v200 offset:34848
